# residual epilogue: lane pairs swap accumulator pieces (v_permlane16_swap) so H is read and written with 16-byte accesses
# speedup vs baseline: 1.0407x; 1.0129x over previous
; __device__ __forceinline__ unsigned cvt_pk_bf16(float lo, float hi) { unsigned r; asm volatile("v_cvt_pk_bf16_f32 %0, %1, %2" : "=v"(r) : "v"(lo), "v"(hi)); return r; }
; __device__ __forceinline__ float ebflo(unsigned w) { return __uint_as_float(w << 16); }
; __device__ __forceinline__ float ebfhi(unsigned w) { return __uint_as_float(w & 0xffff0000u); }
;     __device__ __forceinline__ void operator()(const f32x4 (&acc)[2][2][4][2], const Unit& u, int wr, int wc, int fr, int fq) const {
;         const int row0 = u.pm * BM + wr * 64 + fr, col0 = u.pn * BM + wc * 32 + 4 * fq;
; #pragma unroll
;         for (int ai = 0; ai < 2; ++ai)
; #pragma unroll
;             for (int m = 0; m < 4; ++m) { bf16_t* rowp = H + (size_t)(row0 + ai * HALF + m * 16) * 1024 + col0;
; #pragma unroll
;                 for (int bj = 0; bj < 2; ++bj)
; #pragma unroll
;                     for (int n = 0; n < 2; ++n) { u32x2* q = (u32x2*)(rowp + bj * HALF + n * 16); const u32x2 hv = *q; const f32x4 a = acc[ai][bj][m][n];
;                         u32x2 w; w.x = cvt_pk_bf16(ebflo(hv.x) + a[0], ebfhi(hv.x) + a[1]); w.y = cvt_pk_bf16(ebflo(hv.y) + a[2], ebfhi(hv.y) + a[3]); *q = w; } }
;     }
.LBB0_650:
	s_andn2_b64 vcc, exec, s[10:11]
	s_cbranch_vccnz .LBB0_652
	v_lshl_or_b32 v146, s78, 8, v166
	v_ashrrev_i32_e32 v147, 31, v146
	v_lshlrev_b64 v[148:149], 11, v[144:145]
	v_lshl_add_u64 v[150:151], s[36:37], 0, v[148:149]
	v_lshlrev_b64 v[148:149], 1, v[146:147]
	v_lshl_add_u64 v[146:147], v[150:151], 0, v[148:149]
	v_mbcnt_lo_u32_b32 v160, -1, 0
	v_mbcnt_hi_u32_b32 v160, -1, v160
	v_and_b32_e32 v160, 16, v160
	v_lshrrev_b32_e32 v161, 1, v160
	v_add_u32_e32 v160, v160, v161
	v_mov_b32_e32 v161, 0
	v_lshl_add_u64 v[146:147], v[146:147], 0, v[160:161]
	global_load_dwordx4 v[190:193], v[146:147], off
	global_load_dwordx4 v[194:197], v[146:147], off offset:256
	s_mov_b64 s[10:11], 0x8000
	v_lshl_add_u64 v[148:149], v[146:147], 0, s[10:11]
	global_load_dwordx4 v[198:201], v[148:149], off
	global_load_dwordx4 v[202:205], v[148:149], off offset:256
	s_mov_b64 s[10:11], 0x10000
	v_lshl_add_u64 v[148:149], v[146:147], 0, s[10:11]
	global_load_dwordx4 v[206:209], v[148:149], off
	global_load_dwordx4 v[210:213], v[148:149], off offset:256
	s_mov_b64 s[10:11], 0x18000
	v_lshl_add_u64 v[148:149], v[146:147], 0, s[10:11]
	global_load_dwordx4 v[214:217], v[148:149], off
	global_load_dwordx4 v[218:221], v[148:149], off offset:256
	s_mov_b64 s[10:11], 0x40000
	v_lshl_add_u64 v[148:149], v[146:147], 0, s[10:11]
	global_load_dwordx4 v[222:225], v[148:149], off
	global_load_dwordx4 v[226:229], v[148:149], off offset:256
	s_mov_b64 s[10:11], 0x48000
	v_lshl_add_u64 v[148:149], v[146:147], 0, s[10:11]
	global_load_dwordx4 v[230:233], v[148:149], off
	global_load_dwordx4 v[234:237], v[148:149], off offset:256
	s_mov_b64 s[10:11], 0x50000
	v_lshl_add_u64 v[148:149], v[146:147], 0, s[10:11]
	global_load_dwordx4 v[238:241], v[148:149], off
	global_load_dwordx4 v[242:245], v[148:149], off offset:256
	s_mov_b64 s[10:11], 0x58000
	v_lshl_add_u64 v[148:149], v[146:147], 0, s[10:11]
	global_load_dwordx4 v[152:155], v[148:149], off
	global_load_dwordx4 v[156:159], v[148:149], off offset:256
	s_waitcnt vmcnt(0)
	v_permlane16_swap_b32_e32 v128, v124
	v_permlane16_swap_b32_e32 v129, v125
	v_permlane16_swap_b32_e32 v130, v126
	v_permlane16_swap_b32_e32 v131, v127
	v_lshlrev_b32_e32 v150, 16, v190
	v_and_b32_e32 v151, 0xffff0000, v190
	v_add_f32_e32 v150, v128, v150
	v_add_f32_e32 v151, v129, v151
	v_lshlrev_b32_e32 v160, 16, v191
	v_and_b32_e32 v161, 0xffff0000, v191
	v_cvt_pk_bf16_f32 v190, v150, v151
	v_add_f32_e32 v160, v130, v160
	v_add_f32_e32 v161, v131, v161
	s_nop 0
	v_cvt_pk_bf16_f32 v191, v160, v161
	v_lshlrev_b32_e32 v150, 16, v192
	v_and_b32_e32 v151, 0xffff0000, v192
	v_add_f32_e32 v150, v124, v150
	v_add_f32_e32 v151, v125, v151
	v_lshlrev_b32_e32 v160, 16, v193
	v_and_b32_e32 v161, 0xffff0000, v193
	v_cvt_pk_bf16_f32 v192, v150, v151
	v_add_f32_e32 v160, v126, v160
	v_add_f32_e32 v161, v127, v161
	s_nop 0
	v_cvt_pk_bf16_f32 v193, v160, v161
	s_nop 0
	global_store_dwordx4 v[146:147], v[190:193], off
	v_permlane16_swap_b32_e32 v120, v116
	v_permlane16_swap_b32_e32 v121, v117
	v_permlane16_swap_b32_e32 v122, v118
	v_permlane16_swap_b32_e32 v123, v119
	v_lshlrev_b32_e32 v150, 16, v194
	v_and_b32_e32 v151, 0xffff0000, v194
	v_add_f32_e32 v150, v120, v150
	v_add_f32_e32 v151, v121, v151
	v_lshlrev_b32_e32 v160, 16, v195
	v_and_b32_e32 v161, 0xffff0000, v195
	v_cvt_pk_bf16_f32 v194, v150, v151
	v_add_f32_e32 v160, v122, v160
	v_add_f32_e32 v161, v123, v161
	s_nop 0
	v_cvt_pk_bf16_f32 v195, v160, v161
	v_lshlrev_b32_e32 v150, 16, v196
	v_and_b32_e32 v151, 0xffff0000, v196
	v_add_f32_e32 v150, v116, v150
	v_add_f32_e32 v151, v117, v151
	v_lshlrev_b32_e32 v160, 16, v197
	v_and_b32_e32 v161, 0xffff0000, v197
	v_cvt_pk_bf16_f32 v196, v150, v151
	v_add_f32_e32 v160, v118, v160
	v_add_f32_e32 v161, v119, v161
	s_nop 0
	v_cvt_pk_bf16_f32 v197, v160, v161
	s_nop 0
	global_store_dwordx4 v[146:147], v[194:197], off offset:256
	s_mov_b64 s[10:11], 0x8000
	v_lshl_add_u64 v[148:149], v[146:147], 0, s[10:11]
	v_permlane16_swap_b32_e32 v112, v108
	v_permlane16_swap_b32_e32 v113, v109
	v_permlane16_swap_b32_e32 v114, v110
	v_permlane16_swap_b32_e32 v115, v111
	v_lshlrev_b32_e32 v150, 16, v198
	v_and_b32_e32 v151, 0xffff0000, v198
	v_add_f32_e32 v150, v112, v150
	v_add_f32_e32 v151, v113, v151
	v_lshlrev_b32_e32 v160, 16, v199
	v_and_b32_e32 v161, 0xffff0000, v199
	v_cvt_pk_bf16_f32 v198, v150, v151
	v_add_f32_e32 v160, v114, v160
	v_add_f32_e32 v161, v115, v161
	s_nop 0
	v_cvt_pk_bf16_f32 v199, v160, v161
	v_lshlrev_b32_e32 v150, 16, v200
	v_and_b32_e32 v151, 0xffff0000, v200
	v_add_f32_e32 v150, v108, v150
	v_add_f32_e32 v151, v109, v151
	v_lshlrev_b32_e32 v160, 16, v201
	v_and_b32_e32 v161, 0xffff0000, v201
	v_cvt_pk_bf16_f32 v200, v150, v151
	v_add_f32_e32 v160, v110, v160
	v_add_f32_e32 v161, v111, v161
	s_nop 0
	v_cvt_pk_bf16_f32 v201, v160, v161
	s_nop 0
	global_store_dwordx4 v[148:149], v[198:201], off
	v_permlane16_swap_b32_e32 v104, v100
	v_permlane16_swap_b32_e32 v105, v101
	v_permlane16_swap_b32_e32 v106, v102
	v_permlane16_swap_b32_e32 v107, v103
	v_lshlrev_b32_e32 v150, 16, v202
	v_and_b32_e32 v151, 0xffff0000, v202
	v_add_f32_e32 v150, v104, v150
	v_add_f32_e32 v151, v105, v151
	v_lshlrev_b32_e32 v160, 16, v203
	v_and_b32_e32 v161, 0xffff0000, v203
	v_cvt_pk_bf16_f32 v202, v150, v151
	v_add_f32_e32 v160, v106, v160
	v_add_f32_e32 v161, v107, v161
	s_nop 0
	v_cvt_pk_bf16_f32 v203, v160, v161
	v_lshlrev_b32_e32 v150, 16, v204
	v_and_b32_e32 v151, 0xffff0000, v204
	v_add_f32_e32 v150, v100, v150
	v_add_f32_e32 v151, v101, v151
	v_lshlrev_b32_e32 v160, 16, v205
	v_and_b32_e32 v161, 0xffff0000, v205
	v_cvt_pk_bf16_f32 v204, v150, v151
	v_add_f32_e32 v160, v102, v160
; __device__ __forceinline__ unsigned cvt_pk_bf16(float lo, float hi) { unsigned r; asm volatile("v_cvt_pk_bf16_f32 %0, %1, %2" : "=v"(r) : "v"(lo), "v"(hi)); return r; }
; __device__ __forceinline__ float ebflo(unsigned w) { return __uint_as_float(w << 16); }
; __device__ __forceinline__ float ebfhi(unsigned w) { return __uint_as_float(w & 0xffff0000u); }
;     __device__ __forceinline__ void operator()(const f32x4 (&acc)[2][2][4][2], const Unit& u, int wr, int wc, int fr, int fq) const {
;         const int row0 = u.pm * BM + wr * 64 + fr, col0 = u.pn * BM + wc * 32 + 4 * fq;
; #pragma unroll
;         for (int ai = 0; ai < 2; ++ai)
; #pragma unroll
;             for (int m = 0; m < 4; ++m) { bf16_t* rowp = H + (size_t)(row0 + ai * HALF + m * 16) * 1024 + col0;
; #pragma unroll
;                 for (int bj = 0; bj < 2; ++bj)
; #pragma unroll
;                     for (int n = 0; n < 2; ++n) { u32x2* q = (u32x2*)(rowp + bj * HALF + n * 16); const u32x2 hv = *q; const f32x4 a = acc[ai][bj][m][n];
;                         u32x2 w; w.x = cvt_pk_bf16(ebflo(hv.x) + a[0], ebfhi(hv.x) + a[1]); w.y = cvt_pk_bf16(ebflo(hv.y) + a[2], ebfhi(hv.y) + a[3]); *q = w; } }
;     }
	v_add_f32_e32 v161, v103, v161
	s_nop 0
	v_cvt_pk_bf16_f32 v205, v160, v161
	s_nop 0
	global_store_dwordx4 v[148:149], v[202:205], off offset:256
	s_mov_b64 s[10:11], 0x10000
	v_lshl_add_u64 v[148:149], v[146:147], 0, s[10:11]
	v_permlane16_swap_b32_e32 v96, v92
	v_permlane16_swap_b32_e32 v97, v93
	v_permlane16_swap_b32_e32 v98, v94
	v_permlane16_swap_b32_e32 v99, v95
	v_lshlrev_b32_e32 v150, 16, v206
	v_and_b32_e32 v151, 0xffff0000, v206
	v_add_f32_e32 v150, v96, v150
	v_add_f32_e32 v151, v97, v151
	v_lshlrev_b32_e32 v160, 16, v207
	v_and_b32_e32 v161, 0xffff0000, v207
	v_cvt_pk_bf16_f32 v206, v150, v151
	v_add_f32_e32 v160, v98, v160
	v_add_f32_e32 v161, v99, v161
	s_nop 0
	v_cvt_pk_bf16_f32 v207, v160, v161
	v_lshlrev_b32_e32 v150, 16, v208
	v_and_b32_e32 v151, 0xffff0000, v208
	v_add_f32_e32 v150, v92, v150
	v_add_f32_e32 v151, v93, v151
	v_lshlrev_b32_e32 v160, 16, v209
	v_and_b32_e32 v161, 0xffff0000, v209
	v_cvt_pk_bf16_f32 v208, v150, v151
	v_add_f32_e32 v160, v94, v160
	v_add_f32_e32 v161, v95, v161
	s_nop 0
	v_cvt_pk_bf16_f32 v209, v160, v161
	s_nop 0
	global_store_dwordx4 v[148:149], v[206:209], off
	v_permlane16_swap_b32_e32 v88, v84
	v_permlane16_swap_b32_e32 v89, v85
	v_permlane16_swap_b32_e32 v90, v86
	v_permlane16_swap_b32_e32 v91, v87
	v_lshlrev_b32_e32 v150, 16, v210
	v_and_b32_e32 v151, 0xffff0000, v210
	v_add_f32_e32 v150, v88, v150
	v_add_f32_e32 v151, v89, v151
	v_lshlrev_b32_e32 v160, 16, v211
	v_and_b32_e32 v161, 0xffff0000, v211
	v_cvt_pk_bf16_f32 v210, v150, v151
	v_add_f32_e32 v160, v90, v160
	v_add_f32_e32 v161, v91, v161
	s_nop 0
	v_cvt_pk_bf16_f32 v211, v160, v161
	v_lshlrev_b32_e32 v150, 16, v212
	v_and_b32_e32 v151, 0xffff0000, v212
	v_add_f32_e32 v150, v84, v150
	v_add_f32_e32 v151, v85, v151
	v_lshlrev_b32_e32 v160, 16, v213
	v_and_b32_e32 v161, 0xffff0000, v213
	v_cvt_pk_bf16_f32 v212, v150, v151
	v_add_f32_e32 v160, v86, v160
	v_add_f32_e32 v161, v87, v161
	s_nop 0
	v_cvt_pk_bf16_f32 v213, v160, v161
	s_nop 0
	global_store_dwordx4 v[148:149], v[210:213], off offset:256
	s_mov_b64 s[10:11], 0x18000
	v_lshl_add_u64 v[148:149], v[146:147], 0, s[10:11]
	v_permlane16_swap_b32_e32 v80, v76
	v_permlane16_swap_b32_e32 v81, v77
	v_permlane16_swap_b32_e32 v82, v78
	v_permlane16_swap_b32_e32 v83, v79
	v_lshlrev_b32_e32 v150, 16, v214
	v_and_b32_e32 v151, 0xffff0000, v214
	v_add_f32_e32 v150, v80, v150
	v_add_f32_e32 v151, v81, v151
	v_lshlrev_b32_e32 v160, 16, v215
	v_and_b32_e32 v161, 0xffff0000, v215
	v_cvt_pk_bf16_f32 v214, v150, v151
	v_add_f32_e32 v160, v82, v160
	v_add_f32_e32 v161, v83, v161
	s_nop 0
	v_cvt_pk_bf16_f32 v215, v160, v161
	v_lshlrev_b32_e32 v150, 16, v216
	v_and_b32_e32 v151, 0xffff0000, v216
	v_add_f32_e32 v150, v76, v150
	v_add_f32_e32 v151, v77, v151
	v_lshlrev_b32_e32 v160, 16, v217
	v_and_b32_e32 v161, 0xffff0000, v217
	v_cvt_pk_bf16_f32 v216, v150, v151
	v_add_f32_e32 v160, v78, v160
	v_add_f32_e32 v161, v79, v161
	s_nop 0
	v_cvt_pk_bf16_f32 v217, v160, v161
	s_nop 0
	global_store_dwordx4 v[148:149], v[214:217], off
	v_permlane16_swap_b32_e32 v72, v68
	v_permlane16_swap_b32_e32 v73, v69
	v_permlane16_swap_b32_e32 v74, v70
	v_permlane16_swap_b32_e32 v75, v71
	v_lshlrev_b32_e32 v150, 16, v218
	v_and_b32_e32 v151, 0xffff0000, v218
	v_add_f32_e32 v150, v72, v150
	v_add_f32_e32 v151, v73, v151
	v_lshlrev_b32_e32 v160, 16, v219
	v_and_b32_e32 v161, 0xffff0000, v219
	v_cvt_pk_bf16_f32 v218, v150, v151
	v_add_f32_e32 v160, v74, v160
	v_add_f32_e32 v161, v75, v161
	s_nop 0
	v_cvt_pk_bf16_f32 v219, v160, v161
	v_lshlrev_b32_e32 v150, 16, v220
	v_and_b32_e32 v151, 0xffff0000, v220
	v_add_f32_e32 v150, v68, v150
	v_add_f32_e32 v151, v69, v151
	v_lshlrev_b32_e32 v160, 16, v221
	v_and_b32_e32 v161, 0xffff0000, v221
	v_cvt_pk_bf16_f32 v220, v150, v151
	v_add_f32_e32 v160, v70, v160
	v_add_f32_e32 v161, v71, v161
	s_nop 0
	v_cvt_pk_bf16_f32 v221, v160, v161
	s_nop 0
	global_store_dwordx4 v[148:149], v[218:221], off offset:256
	s_mov_b64 s[10:11], 0x40000
	v_lshl_add_u64 v[148:149], v[146:147], 0, s[10:11]
	v_permlane16_swap_b32_e32 v64, v60
	v_permlane16_swap_b32_e32 v65, v61
	v_permlane16_swap_b32_e32 v66, v62
	v_permlane16_swap_b32_e32 v67, v63
	v_lshlrev_b32_e32 v150, 16, v222
	v_and_b32_e32 v151, 0xffff0000, v222
	v_add_f32_e32 v150, v64, v150
	v_add_f32_e32 v151, v65, v151
	v_lshlrev_b32_e32 v160, 16, v223
	v_and_b32_e32 v161, 0xffff0000, v223
	v_cvt_pk_bf16_f32 v222, v150, v151
	v_add_f32_e32 v160, v66, v160
	v_add_f32_e32 v161, v67, v161
	s_nop 0
	v_cvt_pk_bf16_f32 v223, v160, v161
	v_lshlrev_b32_e32 v150, 16, v224
	v_and_b32_e32 v151, 0xffff0000, v224
	v_add_f32_e32 v150, v60, v150
	v_add_f32_e32 v151, v61, v151
	v_lshlrev_b32_e32 v160, 16, v225
	v_and_b32_e32 v161, 0xffff0000, v225
	v_cvt_pk_bf16_f32 v224, v150, v151
	v_add_f32_e32 v160, v62, v160
	v_add_f32_e32 v161, v63, v161
	s_nop 0
	v_cvt_pk_bf16_f32 v225, v160, v161
	s_nop 0
	global_store_dwordx4 v[148:149], v[222:225], off
	v_permlane16_swap_b32_e32 v56, v52
	v_permlane16_swap_b32_e32 v57, v53
	v_permlane16_swap_b32_e32 v58, v54
	v_permlane16_swap_b32_e32 v59, v55
	v_lshlrev_b32_e32 v150, 16, v226
	v_and_b32_e32 v151, 0xffff0000, v226
	v_add_f32_e32 v150, v56, v150
	v_add_f32_e32 v151, v57, v151
	v_lshlrev_b32_e32 v160, 16, v227
	v_and_b32_e32 v161, 0xffff0000, v227
	v_cvt_pk_bf16_f32 v226, v150, v151
	v_add_f32_e32 v160, v58, v160
	v_add_f32_e32 v161, v59, v161
	s_nop 0
	v_cvt_pk_bf16_f32 v227, v160, v161
	v_lshlrev_b32_e32 v150, 16, v228
	v_and_b32_e32 v151, 0xffff0000, v228
	v_add_f32_e32 v150, v52, v150
	v_add_f32_e32 v151, v53, v151
	v_lshlrev_b32_e32 v160, 16, v229
	v_and_b32_e32 v161, 0xffff0000, v229
	v_cvt_pk_bf16_f32 v228, v150, v151
; __device__ __forceinline__ unsigned cvt_pk_bf16(float lo, float hi) { unsigned r; asm volatile("v_cvt_pk_bf16_f32 %0, %1, %2" : "=v"(r) : "v"(lo), "v"(hi)); return r; }
; __device__ __forceinline__ float ebflo(unsigned w) { return __uint_as_float(w << 16); }
; __device__ __forceinline__ float ebfhi(unsigned w) { return __uint_as_float(w & 0xffff0000u); }
;     __device__ __forceinline__ void operator()(const f32x4 (&acc)[2][2][4][2], const Unit& u, int wr, int wc, int fr, int fq) const {
;     ...
;             for (int m = 0; m < 4; ++m) { bf16_t* rowp = H + (size_t)(row0 + ai * HALF + m * 16) * 1024 + col0;
; #pragma unroll
;                 for (int bj = 0; bj < 2; ++bj)
; #pragma unroll
;                     for (int n = 0; n < 2; ++n) { u32x2* q = (u32x2*)(rowp + bj * HALF + n * 16); const u32x2 hv = *q; const f32x4 a = acc[ai][bj][m][n];
;                         u32x2 w; w.x = cvt_pk_bf16(ebflo(hv.x) + a[0], ebfhi(hv.x) + a[1]); w.y = cvt_pk_bf16(ebflo(hv.y) + a[2], ebfhi(hv.y) + a[3]); *q = w; } }
	v_add_f32_e32 v160, v54, v160
	v_add_f32_e32 v161, v55, v161
	s_nop 0
	v_cvt_pk_bf16_f32 v229, v160, v161
	s_nop 0
	global_store_dwordx4 v[148:149], v[226:229], off offset:256
	s_mov_b64 s[10:11], 0x48000
	v_lshl_add_u64 v[148:149], v[146:147], 0, s[10:11]
	v_permlane16_swap_b32_e32 v48, v44
	v_permlane16_swap_b32_e32 v49, v45
	v_permlane16_swap_b32_e32 v50, v46
	v_permlane16_swap_b32_e32 v51, v47
	v_lshlrev_b32_e32 v150, 16, v230
	v_and_b32_e32 v151, 0xffff0000, v230
	v_add_f32_e32 v150, v48, v150
	v_add_f32_e32 v151, v49, v151
	v_lshlrev_b32_e32 v160, 16, v231
	v_and_b32_e32 v161, 0xffff0000, v231
	v_cvt_pk_bf16_f32 v230, v150, v151
	v_add_f32_e32 v160, v50, v160
	v_add_f32_e32 v161, v51, v161
	s_nop 0
	v_cvt_pk_bf16_f32 v231, v160, v161
	v_lshlrev_b32_e32 v150, 16, v232
	v_and_b32_e32 v151, 0xffff0000, v232
	v_add_f32_e32 v150, v44, v150
	v_add_f32_e32 v151, v45, v151
	v_lshlrev_b32_e32 v160, 16, v233
	v_and_b32_e32 v161, 0xffff0000, v233
	v_cvt_pk_bf16_f32 v232, v150, v151
	v_add_f32_e32 v160, v46, v160
	v_add_f32_e32 v161, v47, v161
	s_nop 0
	v_cvt_pk_bf16_f32 v233, v160, v161
	s_nop 0
	global_store_dwordx4 v[148:149], v[230:233], off
	v_permlane16_swap_b32_e32 v40, v36
	v_permlane16_swap_b32_e32 v41, v37
	v_permlane16_swap_b32_e32 v42, v38
	v_permlane16_swap_b32_e32 v43, v39
	v_lshlrev_b32_e32 v150, 16, v234
	v_and_b32_e32 v151, 0xffff0000, v234
	v_add_f32_e32 v150, v40, v150
	v_add_f32_e32 v151, v41, v151
	v_lshlrev_b32_e32 v160, 16, v235
	v_and_b32_e32 v161, 0xffff0000, v235
	v_cvt_pk_bf16_f32 v234, v150, v151
	v_add_f32_e32 v160, v42, v160
	v_add_f32_e32 v161, v43, v161
	s_nop 0
	v_cvt_pk_bf16_f32 v235, v160, v161
	v_lshlrev_b32_e32 v150, 16, v236
	v_and_b32_e32 v151, 0xffff0000, v236
	v_add_f32_e32 v150, v36, v150
	v_add_f32_e32 v151, v37, v151
	v_lshlrev_b32_e32 v160, 16, v237
	v_and_b32_e32 v161, 0xffff0000, v237
	v_cvt_pk_bf16_f32 v236, v150, v151
	v_add_f32_e32 v160, v38, v160
	v_add_f32_e32 v161, v39, v161
	s_nop 0
	v_cvt_pk_bf16_f32 v237, v160, v161
	s_nop 0
	global_store_dwordx4 v[148:149], v[234:237], off offset:256
	s_mov_b64 s[10:11], 0x50000
	v_lshl_add_u64 v[148:149], v[146:147], 0, s[10:11]
	v_permlane16_swap_b32_e32 v32, v28
	v_permlane16_swap_b32_e32 v33, v29
	v_permlane16_swap_b32_e32 v34, v30
	v_permlane16_swap_b32_e32 v35, v31
	v_lshlrev_b32_e32 v150, 16, v238
	v_and_b32_e32 v151, 0xffff0000, v238
	v_add_f32_e32 v150, v32, v150
	v_add_f32_e32 v151, v33, v151
	v_lshlrev_b32_e32 v160, 16, v239
	v_and_b32_e32 v161, 0xffff0000, v239
	v_cvt_pk_bf16_f32 v238, v150, v151
	v_add_f32_e32 v160, v34, v160
	v_add_f32_e32 v161, v35, v161
	s_nop 0
	v_cvt_pk_bf16_f32 v239, v160, v161
	v_lshlrev_b32_e32 v150, 16, v240
	v_and_b32_e32 v151, 0xffff0000, v240
	v_add_f32_e32 v150, v28, v150
	v_add_f32_e32 v151, v29, v151
	v_lshlrev_b32_e32 v160, 16, v241
	v_and_b32_e32 v161, 0xffff0000, v241
	v_cvt_pk_bf16_f32 v240, v150, v151
	v_add_f32_e32 v160, v30, v160
	v_add_f32_e32 v161, v31, v161
	s_nop 0
	v_cvt_pk_bf16_f32 v241, v160, v161
	s_nop 0
	global_store_dwordx4 v[148:149], v[238:241], off
	v_permlane16_swap_b32_e32 v24, v20
	v_permlane16_swap_b32_e32 v25, v21
	v_permlane16_swap_b32_e32 v26, v22
	v_permlane16_swap_b32_e32 v27, v23
	v_lshlrev_b32_e32 v150, 16, v242
	v_and_b32_e32 v151, 0xffff0000, v242
	v_add_f32_e32 v150, v24, v150
	v_add_f32_e32 v151, v25, v151
	v_lshlrev_b32_e32 v160, 16, v243
	v_and_b32_e32 v161, 0xffff0000, v243
	v_cvt_pk_bf16_f32 v242, v150, v151
	v_add_f32_e32 v160, v26, v160
	v_add_f32_e32 v161, v27, v161
	s_nop 0
	v_cvt_pk_bf16_f32 v243, v160, v161
	v_lshlrev_b32_e32 v150, 16, v244
	v_and_b32_e32 v151, 0xffff0000, v244
	v_add_f32_e32 v150, v20, v150
	v_add_f32_e32 v151, v21, v151
	v_lshlrev_b32_e32 v160, 16, v245
	v_and_b32_e32 v161, 0xffff0000, v245
	v_cvt_pk_bf16_f32 v244, v150, v151
	v_add_f32_e32 v160, v22, v160
	v_add_f32_e32 v161, v23, v161
	s_nop 0
	v_cvt_pk_bf16_f32 v245, v160, v161
	s_nop 0
	global_store_dwordx4 v[148:149], v[242:245], off offset:256
	s_mov_b64 s[10:11], 0x58000
	v_lshl_add_u64 v[148:149], v[146:147], 0, s[10:11]
	v_permlane16_swap_b32_e32 v16, v12
	v_permlane16_swap_b32_e32 v17, v13
	v_permlane16_swap_b32_e32 v18, v14
	v_permlane16_swap_b32_e32 v19, v15
	v_lshlrev_b32_e32 v150, 16, v152
	v_and_b32_e32 v151, 0xffff0000, v152
	v_add_f32_e32 v150, v16, v150
	v_add_f32_e32 v151, v17, v151
	v_lshlrev_b32_e32 v160, 16, v153
	v_and_b32_e32 v161, 0xffff0000, v153
	v_cvt_pk_bf16_f32 v152, v150, v151
	v_add_f32_e32 v160, v18, v160
	v_add_f32_e32 v161, v19, v161
	s_nop 0
	v_cvt_pk_bf16_f32 v153, v160, v161
	v_lshlrev_b32_e32 v150, 16, v154
	v_and_b32_e32 v151, 0xffff0000, v154
	v_add_f32_e32 v150, v12, v150
	v_add_f32_e32 v151, v13, v151
	v_lshlrev_b32_e32 v160, 16, v155
	v_and_b32_e32 v161, 0xffff0000, v155
	v_cvt_pk_bf16_f32 v154, v150, v151
	v_add_f32_e32 v160, v14, v160
	v_add_f32_e32 v161, v15, v161
	s_nop 0
	v_cvt_pk_bf16_f32 v155, v160, v161
	s_nop 0
	global_store_dwordx4 v[148:149], v[152:155], off
	v_permlane16_swap_b32_e32 v8, v4
	v_permlane16_swap_b32_e32 v9, v5
	v_permlane16_swap_b32_e32 v10, v6
	v_permlane16_swap_b32_e32 v11, v7
	v_lshlrev_b32_e32 v150, 16, v156
	v_and_b32_e32 v151, 0xffff0000, v156
	v_add_f32_e32 v150, v8, v150
	v_add_f32_e32 v151, v9, v151
	v_lshlrev_b32_e32 v160, 16, v157
	v_and_b32_e32 v161, 0xffff0000, v157
	v_cvt_pk_bf16_f32 v156, v150, v151
	v_add_f32_e32 v160, v10, v160
	v_add_f32_e32 v161, v11, v161
	s_nop 0
	v_cvt_pk_bf16_f32 v157, v160, v161
	v_lshlrev_b32_e32 v150, 16, v158
	v_and_b32_e32 v151, 0xffff0000, v158
	v_add_f32_e32 v150, v4, v150
	v_add_f32_e32 v151, v5, v151
	v_lshlrev_b32_e32 v160, 16, v159
	v_and_b32_e32 v161, 0xffff0000, v159
	v_cvt_pk_bf16_f32 v158, v150, v151
	v_add_f32_e32 v160, v6, v160
	v_add_f32_e32 v161, v7, v161
	s_nop 0
	v_cvt_pk_bf16_f32 v159, v160, v161
	s_nop 0
	global_store_dwordx4 v[148:149], v[156:159], off offset:256
	s_mov_b64 s[10:11], 0x58000
